# all three sample-row skinny GEMMs (out/up/down) hand-pipelined; XG and U sample rows kept fragment-linear between producer and consumer so A loads are 1KB contiguous
# speedup vs baseline: 1.0249x; 1.0128x over previous
; #define LAS __attribute__((address_space(3)))
; #define SK_LOAD(buf, c) do { _Pragma("unroll") for (int nt = 0; nt < 2; ++nt) fb[buf][nt] = *(const bf16x8*)(pb + nt * rs + 32 * (c)); \
;         _Pragma("unroll") for (int mt = 0; mt < NMT; ++mt) fa[buf][mt] = *(const bf16x8*)(pa + mt * rs + 32 * (c)); } while (0)
; #define SK_MMA(buf) do { _Pragma("unroll") for (int mt = 0; mt < NMT; ++mt) _Pragma("unroll") for (int nt = 0; nt < 2; ++nt) \
;         acc[mt][nt] = __builtin_amdgcn_mfma_f32_16x16x32_bf16(fa[buf][mt], fb[buf][nt], acc[mt][nt], 0, 0, 0); } while (0)
; template <int MT, class Epi>
; DI void skinny_unit(LAS unsigned char* lds, const bf16_t* A, const bf16_t* Wt, int K, int cgi, int k0, int row0, const Epi& E, int tid) {
;     const int lane = tid & 63, wid = tid >> 6, fr = lane & 15, fq = lane >> 4;
;     const int c0 = cgi * 32;
;     constexpr int NMT = 2 * MT;
;     const bf16_t* pa = A + (size_t)(row0 + fr) * K + k0 + wid * 256 + 8 * fq;
;     const bf16_t* pb = Wt + (size_t)(c0 + fr) * K + k0 + wid * 256 + 8 * fq;
;     const size_t rs = (size_t)16 * K;
;     f32x4 acc[NMT][2];
; #pragma unroll
;     for (int i = 0; i < NMT; ++i) { acc[i][0] = (f32x4){0.f, 0.f, 0.f, 0.f}; acc[i][1] = (f32x4){0.f, 0.f, 0.f, 0.f}; }
;     bf16x8 fb[3][2], fa[3][NMT];
;     ...
;     SK_LOAD(0, 0); SK_LOAD(1, 1);
;     SK_LOAD(2, 2); SK_MMA(0);
;     SK_LOAD(0, 3); SK_MMA(1);
;     SK_LOAD(1, 4); SK_MMA(2);
;     SK_LOAD(2, 5); SK_MMA(0);
;     SK_LOAD(0, 6); SK_MMA(1);
;     SK_LOAD(1, 7); SK_MMA(2);
;     SK_MMA(0); SK_MMA(1);
; __global__ void __launch_bounds__(512, 2) fwd_kernel(Args a) {
;     ...
;         for (int u = bx; u < 4 * (DM / 32); u += G) skinny_unit<1>(lds, MIX + (size_t)LP * DM, WOUT, DM, u >> 2, 0, (u & 3) * 32, SE, tid);
.LBB0_549:
	s_waitcnt vmcnt(0)
	s_waitcnt lgkmcnt(0)
	s_barrier
	s_mov_b64 exec, -1
	v_readlane_b32 s16, v254, 15
	v_readlane_b32 s17, v254, 16
	v_readlane_b32 s18, v254, 17
	v_readlane_b32 s19, v254, 18
	v_readlane_b32 s20, v254, 19
	v_readlane_b32 s21, v254, 20
	v_readlane_b32 s22, v254, 21
	v_readlane_b32 s23, v254, 22
	v_and_b32_e32 v20, 15, v253
	v_bfe_u32 v21, v253, 4, 2
	v_lshrrev_b32_e32 v22, 6, v253
	v_lshlrev_b32_e32 v16, 12, v20
	v_lshl_add_u32 v16, v22, 9, v16
	v_lshl_add_u32 v16, v21, 4, v16
	v_readfirstlane_b32 s1, v22
	v_lshlrev_b32_e32 v17, 12, v22
	v_lshl_add_u32 v17, v21, 9, v17
	v_lshl_add_u32 v17, v20, 2, v17
	v_lshrrev_b32_e32 v23, 3, v253
	v_and_b32_e32 v24, 7, v253
	v_lshlrev_b32_e32 v18, 7, v23
	v_lshl_add_u32 v18, v24, 4, v18
	v_lshlrev_b32_e32 v19, 13, v23
	v_lshl_add_u32 v19, v24, 4, v19
	v_lshrrev_b32_e32 v148, 4, v23
	v_lshlrev_b32_e32 v148, 10, v148
	v_lshrrev_b32_e32 v149, 1, v24
	v_lshl_add_u32 v148, v149, 8, v148
	v_and_b32_e32 v149, 15, v23
	v_lshl_add_u32 v148, v149, 4, v148
	v_and_b32_e32 v149, 1, v24
	v_lshl_add_u32 v148, v149, 3, v148
	s_add_u32 s4, s60, 0xa000000
	s_addc_u32 s5, s61, 0
	s_add_u32 s8, s60, 0x1700000
	s_addc_u32 s9, s61, 0
	s_mov_b32 s0, s92
.Lsk5_loop:
	s_and_b32 s2, s0, 3
	s_lshr_b32 s3, s0, 2
	s_lshl_b32 s10, s2, 17
	s_add_u32 s10, s4, s10
	s_addc_u32 s11, s5, 0
	s_add_u32 s12, s10, 0x10000
	s_addc_u32 s13, s11, 0
	s_lshl_b32 s14, s3, 17
	s_add_u32 s14, s8, s14
	s_addc_u32 s15, s9, 0
	s_add_u32 s24, s14, 0x10000
	s_addc_u32 s25, s15, 0
	s_lshl_b32 s28, s2, 18
	s_lshl_b32 s29, s3, 7
	s_add_u32 s28, s28, s29
	s_add_u32 s26, s46, s28
	s_addc_u32 s27, s47, 0
	s_add_u32 s28, s28, 0x4000000
	s_add_u32 s28, s22, s28
	s_addc_u32 s29, s23, 0
	s_lshl_b32 s30, s2, 11
	s_lshl_b32 s31, s3, 13
	s_add_u32 s30, s30, s31
	s_add_u32 s30, s30, 0x7f00000
	s_add_u32 s30, s60, s30
	s_addc_u32 s31, s61, 0
	global_load_dwordx4 v[28:31], v16, s[14:15] offset:0 nt
	global_load_dwordx4 v[44:47], v16, s[14:15] offset:64 nt
	global_load_dwordx4 v[32:35], v16, s[24:25] offset:0 nt
	global_load_dwordx4 v[48:51], v16, s[24:25] offset:64 nt
	global_load_dwordx4 v[20:23], v16, s[10:11] offset:0
	global_load_dwordx4 v[36:39], v16, s[10:11] offset:64
	global_load_dwordx4 v[24:27], v16, s[12:13] offset:0
	global_load_dwordx4 v[40:43], v16, s[12:13] offset:64
	global_load_dwordx4 v[60:63], v16, s[14:15] offset:128 nt
	global_load_dwordx4 v[76:79], v16, s[14:15] offset:192 nt
	global_load_dwordx4 v[64:67], v16, s[24:25] offset:128 nt
	global_load_dwordx4 v[80:83], v16, s[24:25] offset:192 nt
	global_load_dwordx4 v[52:55], v16, s[10:11] offset:128
	global_load_dwordx4 v[68:71], v16, s[10:11] offset:192
	global_load_dwordx4 v[56:59], v16, s[12:13] offset:128
	global_load_dwordx4 v[72:75], v16, s[12:13] offset:192
	global_load_dwordx4 v[92:95], v16, s[14:15] offset:256 nt
	global_load_dwordx4 v[108:111], v16, s[14:15] offset:320 nt
	global_load_dwordx4 v[96:99], v16, s[24:25] offset:256 nt
	global_load_dwordx4 v[112:115], v16, s[24:25] offset:320 nt
	global_load_dwordx4 v[84:87], v16, s[10:11] offset:256
	global_load_dwordx4 v[100:103], v16, s[10:11] offset:320
	global_load_dwordx4 v[88:91], v16, s[12:13] offset:256
	global_load_dwordx4 v[104:107], v16, s[12:13] offset:320
	global_load_dwordx4 v[124:127], v16, s[14:15] offset:384 nt
	global_load_dwordx4 v[140:143], v16, s[14:15] offset:448 nt
	global_load_dwordx4 v[128:131], v16, s[24:25] offset:384 nt
	global_load_dwordx4 v[144:147], v16, s[24:25] offset:448 nt
	global_load_dwordx4 v[116:119], v16, s[10:11] offset:384
	global_load_dwordx4 v[132:135], v16, s[10:11] offset:448
	global_load_dwordx4 v[120:123], v16, s[12:13] offset:384
	global_load_dwordx4 v[136:139], v16, s[12:13] offset:448
	s_waitcnt vmcnt(24)
	v_mfma_f32_16x16x32_bf16 v[0:3], v[20:23], v[28:31], 0
	v_mfma_f32_16x16x32_bf16 v[4:7], v[20:23], v[32:35], 0
	v_mfma_f32_16x16x32_bf16 v[8:11], v[24:27], v[28:31], 0
	v_mfma_f32_16x16x32_bf16 v[12:15], v[24:27], v[32:35], 0
	v_mfma_f32_16x16x32_bf16 v[0:3], v[36:39], v[44:47], v[0:3]
	v_mfma_f32_16x16x32_bf16 v[4:7], v[36:39], v[48:51], v[4:7]
	v_mfma_f32_16x16x32_bf16 v[8:11], v[40:43], v[44:47], v[8:11]
	v_mfma_f32_16x16x32_bf16 v[12:15], v[40:43], v[48:51], v[12:15]
	s_waitcnt vmcnt(16)
	v_mfma_f32_16x16x32_bf16 v[0:3], v[52:55], v[60:63], v[0:3]
	v_mfma_f32_16x16x32_bf16 v[4:7], v[52:55], v[64:67], v[4:7]
	v_mfma_f32_16x16x32_bf16 v[8:11], v[56:59], v[60:63], v[8:11]
	v_mfma_f32_16x16x32_bf16 v[12:15], v[56:59], v[64:67], v[12:15]
	v_mfma_f32_16x16x32_bf16 v[0:3], v[68:71], v[76:79], v[0:3]
	v_mfma_f32_16x16x32_bf16 v[4:7], v[68:71], v[80:83], v[4:7]
	v_mfma_f32_16x16x32_bf16 v[8:11], v[72:75], v[76:79], v[8:11]
	v_mfma_f32_16x16x32_bf16 v[12:15], v[72:75], v[80:83], v[12:15]
	s_waitcnt vmcnt(8)
	v_mfma_f32_16x16x32_bf16 v[0:3], v[84:87], v[92:95], v[0:3]
	v_mfma_f32_16x16x32_bf16 v[4:7], v[84:87], v[96:99], v[4:7]
	v_mfma_f32_16x16x32_bf16 v[8:11], v[88:91], v[92:95], v[8:11]
	v_mfma_f32_16x16x32_bf16 v[12:15], v[88:91], v[96:99], v[12:15]
	v_mfma_f32_16x16x32_bf16 v[0:3], v[100:103], v[108:111], v[0:3]
	v_mfma_f32_16x16x32_bf16 v[4:7], v[100:103], v[112:115], v[4:7]
	v_mfma_f32_16x16x32_bf16 v[8:11], v[104:107], v[108:111], v[8:11]
	v_mfma_f32_16x16x32_bf16 v[12:15], v[104:107], v[112:115], v[12:15]
	s_waitcnt vmcnt(0)
	v_mfma_f32_16x16x32_bf16 v[0:3], v[116:119], v[124:127], v[0:3]
	v_mfma_f32_16x16x32_bf16 v[4:7], v[116:119], v[128:131], v[4:7]
	v_mfma_f32_16x16x32_bf16 v[8:11], v[120:123], v[124:127], v[8:11]
	v_mfma_f32_16x16x32_bf16 v[12:15], v[120:123], v[128:131], v[12:15]
	v_mfma_f32_16x16x32_bf16 v[0:3], v[132:135], v[140:143], v[0:3]
	v_mfma_f32_16x16x32_bf16 v[4:7], v[132:135], v[144:147], v[4:7]
	v_mfma_f32_16x16x32_bf16 v[8:11], v[136:139], v[140:143], v[8:11]
	v_mfma_f32_16x16x32_bf16 v[12:15], v[136:139], v[144:147], v[12:15]
	s_cmp_lt_u32 s1, 4
	s_cbranch_scc0 .Lsk5_nox
	global_load_dwordx4 v[84:87], v19, s[26:27]
; #define LAS __attribute__((address_space(3)))
; template <int MT, class Epi>
; DI void skinny_unit(LAS unsigned char* lds, const bf16_t* A, const bf16_t* Wt, int K, int cgi, int k0, int row0, const Epi& E, int tid) {
;     ...
;     constexpr int NR = 32 * MT;
;     LAS float* red = (LAS float*)lds;
; #pragma unroll
;     for (int mt = 0; mt < NMT; ++mt)
; #pragma unroll
;         for (int nt = 0; nt < 2; ++nt)
; #pragma unroll
;             for (int j = 0; j < 4; ++j) red[(wid * NR + mt * 16 + 4 * fq + j) * 32 + nt * 16 + fr] = acc[mt][nt][j];
;     __syncthreads();
;     if (MT == 4) {
;         const int row = tid >> 2, c8 = (tid & 3) * 8;
;         f32x4 sa = {0.f, 0.f, 0.f, 0.f}, sb = {0.f, 0.f, 0.f, 0.f};
; #pragma unroll
;         for (int w = 0; w < 8; ++w) { sa += *(const LAS f32x4*)(red + (w * NR + row) * 32 + c8); sb += *(const LAS f32x4*)(red + (w * NR + row) * 32 + c8 + 4); }
;         E(row0 + row, c0 + c8, sa); E(row0 + row, c0 + c8 + 4, sb);
;     } else if (tid < 8 * NR) {
;         const int row = tid >> 3, c4 = (tid & 7) * 4;
;         f32x4 sa = {0.f, 0.f, 0.f, 0.f};
; #pragma unroll
;         for (int w = 0; w < 8; ++w) sa += *(const LAS f32x4*)(red + (w * NR + row) * 32 + c4);
;         E(row0 + row, c0 + c4, sa);
;     }
;     __syncthreads();
; }
.Lsk5_nox:
	v_add_u32_e32 v149, 0x800, v17
	s_nop 7
	s_nop 3
	ds_write2_b32 v17, v0, v4 offset1:16
	ds_write2_b32 v17, v1, v5 offset0:32 offset1:48
	ds_write2_b32 v17, v2, v6 offset0:64 offset1:80
	ds_write2_b32 v17, v3, v7 offset0:96 offset1:112
	ds_write2_b32 v149, v8, v12 offset1:16
	ds_write2_b32 v149, v9, v13 offset0:32 offset1:48
	ds_write2_b32 v149, v10, v14 offset0:64 offset1:80
	ds_write2_b32 v149, v11, v15 offset0:96 offset1:112
	s_waitcnt lgkmcnt(0)
	s_barrier
	s_cmp_lt_u32 s1, 4
	s_cbranch_scc0 .Lsk5_skip
	ds_read_b128 v[20:23], v18 offset:0
	ds_read_b128 v[24:27], v18 offset:4096
	ds_read_b128 v[28:31], v18 offset:8192
	ds_read_b128 v[32:35], v18 offset:12288
	ds_read_b128 v[36:39], v18 offset:16384
	ds_read_b128 v[40:43], v18 offset:20480
	ds_read_b128 v[44:47], v18 offset:24576
	ds_read_b128 v[48:51], v18 offset:28672
	s_waitcnt lgkmcnt(6)
	v_pk_add_f32 v[20:21], v[20:21], v[24:25]
	v_pk_add_f32 v[22:23], v[22:23], v[26:27]
	s_waitcnt lgkmcnt(5)
	v_pk_add_f32 v[20:21], v[20:21], v[28:29]
	v_pk_add_f32 v[22:23], v[22:23], v[30:31]
	s_waitcnt lgkmcnt(4)
	v_pk_add_f32 v[20:21], v[20:21], v[32:33]
	v_pk_add_f32 v[22:23], v[22:23], v[34:35]
	s_waitcnt lgkmcnt(3)
	v_pk_add_f32 v[20:21], v[20:21], v[36:37]
	v_pk_add_f32 v[22:23], v[22:23], v[38:39]
	s_waitcnt lgkmcnt(2)
	v_pk_add_f32 v[20:21], v[20:21], v[40:41]
	v_pk_add_f32 v[22:23], v[22:23], v[42:43]
	s_waitcnt lgkmcnt(1)
	v_pk_add_f32 v[20:21], v[20:21], v[44:45]
	v_pk_add_f32 v[22:23], v[22:23], v[46:47]
	s_waitcnt lgkmcnt(0)
	v_pk_add_f32 v[20:21], v[20:21], v[48:49]
	v_pk_add_f32 v[22:23], v[22:23], v[50:51]
	s_waitcnt vmcnt(0)
	v_pk_add_f32 v[20:21], v[20:21], v[84:85]
	v_pk_add_f32 v[22:23], v[22:23], v[86:87]
	global_store_dwordx4 v19, v[20:23], s[28:29]
	v_cvt_pk_bf16_f32 v24, v20, v21
	v_cvt_pk_bf16_f32 v25, v22, v23
	global_store_dwordx2 v148, v[24:25], s[30:31]
.Lsk5_skip:
	s_add_i32 s0, s0, s64
	s_cmpk_lt_i32 s0, 0x100
	s_barrier
	s_cbranch_scc1 .Lsk5_loop

; #define LAS __attribute__((address_space(3)))
; #define SK_LOAD(buf, c) do { _Pragma("unroll") for (int nt = 0; nt < 2; ++nt) fb[buf][nt] = *(const bf16x8*)(pb + nt * rs + 32 * (c)); \
;         _Pragma("unroll") for (int mt = 0; mt < NMT; ++mt) fa[buf][mt] = *(const bf16x8*)(pa + mt * rs + 32 * (c)); } while (0)
; #define SK_MMA(buf) do { _Pragma("unroll") for (int mt = 0; mt < NMT; ++mt) _Pragma("unroll") for (int nt = 0; nt < 2; ++nt) \
;         acc[mt][nt] = __builtin_amdgcn_mfma_f32_16x16x32_bf16(fa[buf][mt], fb[buf][nt], acc[mt][nt], 0, 0, 0); } while (0)
; template <int MT, class Epi>
; DI void skinny_unit(LAS unsigned char* lds, const bf16_t* A, const bf16_t* Wt, int K, int cgi, int k0, int row0, const Epi& E, int tid) {
;     const int lane = tid & 63, wid = tid >> 6, fr = lane & 15, fq = lane >> 4;
;     const int c0 = cgi * 32;
;     constexpr int NMT = 2 * MT;
;     const bf16_t* pa = A + (size_t)(row0 + fr) * K + k0 + wid * 256 + 8 * fq;
;     const bf16_t* pb = Wt + (size_t)(c0 + fr) * K + k0 + wid * 256 + 8 * fq;
;     const size_t rs = (size_t)16 * K;
;     f32x4 acc[NMT][2];
; #pragma unroll
;     for (int i = 0; i < NMT; ++i) { acc[i][0] = (f32x4){0.f, 0.f, 0.f, 0.f}; acc[i][1] = (f32x4){0.f, 0.f, 0.f, 0.f}; }
;     bf16x8 fb[3][2], fa[3][NMT];
;     ...
;     SK_LOAD(0, 0); SK_LOAD(1, 1);
;     SK_LOAD(2, 2); SK_MMA(0);
;     SK_LOAD(0, 3); SK_MMA(1);
;     SK_LOAD(1, 4); SK_MMA(2);
;     SK_LOAD(2, 5); SK_MMA(0);
; __global__ void __launch_bounds__(512, 2) fwd_kernel(Args a) {
;     ...
;         for (int u = bx; u < FF / 32; u += G) skinny_unit<4>(lds, XG + (size_t)LP * DM, WUP, DM, u, 0, 0, SE, tid);
.LBB0_636:
	s_cmpk_gt_i32 s92, 0xff
	s_cbranch_scc1 .LBB0_639
	s_waitcnt lgkmcnt(0)
	s_mov_b64 exec, -1
	v_and_b32_e32 v70, 15, v253
	v_bfe_u32 v71, v253, 4, 2
	v_lshrrev_b32_e32 v72, 6, v253
	v_mul_u32_u24_e32 v64, 0x1000, v70
	v_lshl_add_u32 v64, v72, 9, v64
	v_lshl_add_u32 v64, v71, 4, v64
	v_readfirstlane_b32 s1, v72
	v_and_b32_e32 v69, 63, v253
	v_lshlrev_b32_e32 v69, 4, v69
	v_mul_u32_u24_e32 v65, 0x4000, v72
	v_lshl_add_u32 v65, v71, 9, v65
	v_lshl_add_u32 v65, v70, 2, v65
	v_lshrrev_b32_e32 v73, 2, v253
	v_and_b32_e32 v74, 3, v253
	v_lshlrev_b32_e32 v66, 7, v73
	v_lshl_add_u32 v66, v74, 5, v66
	v_add_u32_e32 v67, 0x10000, v66
	v_and_b32_e32 v68, 15, v73
	v_lshl_add_u32 v68, v74, 4, v68
	v_lshlrev_b32_e32 v68, 4, v68
	v_lshl_add_u32 v68, v72, 10, v68
	s_add_u32 s2, s60, 0x7f00000
	s_addc_u32 s3, s61, 0
	s_add_u32 s6, s60, 0x1f00000
	s_addc_u32 s7, s61, 0
	s_lshl_b32 s1, s1, 16
	s_add_u32 s2, s2, s1
	s_addc_u32 s3, s3, 0
	s_mov_b32 s0, s92
.Lsk6_loop:
	s_mov_b64 s[14:15], s[2:3]
	s_lshl_b32 s8, s0, 17
	s_add_u32 s8, s6, s8
	s_addc_u32 s9, s7, 0
	s_add_u32 s10, s8, 0x10000
	s_addc_u32 s11, s9, 0
	s_lshl_b32 s12, s0, 13
	s_add_u32 s12, s12, 0x12400000
	s_add_u32 s12, s60, s12
	s_addc_u32 s13, s61, 0
	global_load_dwordx4 v[108:111], v64, s[8:9] offset:0 nt
	global_load_dwordx4 v[148:151], v64, s[8:9] offset:64 nt
	global_load_dwordx4 v[112:115], v64, s[10:11] offset:0 nt
	global_load_dwordx4 v[152:155], v64, s[10:11] offset:64 nt
	global_load_dwordx4 v[76:79], v69, s[14:15] offset:0
	global_load_dwordx4 v[80:83], v69, s[14:15] offset:1024
	global_load_dwordx4 v[84:87], v69, s[14:15] offset:2048
	global_load_dwordx4 v[88:91], v69, s[14:15] offset:3072
	s_add_u32 s14, s14, 0x1000
	s_addc_u32 s15, s15, 0
	global_load_dwordx4 v[92:95], v69, s[14:15] offset:0
	global_load_dwordx4 v[96:99], v69, s[14:15] offset:1024
	global_load_dwordx4 v[100:103], v69, s[14:15] offset:2048
	global_load_dwordx4 v[104:107], v69, s[14:15] offset:3072
	s_add_u32 s14, s14, 0x1000
	s_addc_u32 s15, s15, 0
	global_load_dwordx4 v[116:119], v69, s[14:15] offset:0
	global_load_dwordx4 v[120:123], v69, s[14:15] offset:1024
	global_load_dwordx4 v[124:127], v69, s[14:15] offset:2048
	global_load_dwordx4 v[128:131], v69, s[14:15] offset:3072
	s_add_u32 s14, s14, 0x1000
	s_addc_u32 s15, s15, 0
	global_load_dwordx4 v[132:135], v69, s[14:15] offset:0
	global_load_dwordx4 v[136:139], v69, s[14:15] offset:1024
	global_load_dwordx4 v[140:143], v69, s[14:15] offset:2048
	global_load_dwordx4 v[144:147], v69, s[14:15] offset:3072
	s_add_u32 s14, s14, 0x1000
	s_addc_u32 s15, s15, 0
	global_load_dwordx4 v[188:191], v64, s[8:9] offset:128 nt
	global_load_dwordx4 v[228:231], v64, s[8:9] offset:192 nt
	global_load_dwordx4 v[192:195], v64, s[10:11] offset:128 nt
	global_load_dwordx4 v[232:235], v64, s[10:11] offset:192 nt
	global_load_dwordx4 v[156:159], v69, s[14:15] offset:0
	global_load_dwordx4 v[160:163], v69, s[14:15] offset:1024
	global_load_dwordx4 v[164:167], v69, s[14:15] offset:2048
	global_load_dwordx4 v[168:171], v69, s[14:15] offset:3072
	s_add_u32 s14, s14, 0x1000
	s_addc_u32 s15, s15, 0
	global_load_dwordx4 v[172:175], v69, s[14:15] offset:0
	global_load_dwordx4 v[176:179], v69, s[14:15] offset:1024
	global_load_dwordx4 v[180:183], v69, s[14:15] offset:2048
	global_load_dwordx4 v[184:187], v69, s[14:15] offset:3072
	s_add_u32 s14, s14, 0x1000
	s_addc_u32 s15, s15, 0
	global_load_dwordx4 v[196:199], v69, s[14:15] offset:0
	global_load_dwordx4 v[200:203], v69, s[14:15] offset:1024
	global_load_dwordx4 v[204:207], v69, s[14:15] offset:2048
	global_load_dwordx4 v[208:211], v69, s[14:15] offset:3072
	s_add_u32 s14, s14, 0x1000
	s_addc_u32 s15, s15, 0
	global_load_dwordx4 v[212:215], v69, s[14:15] offset:0
	global_load_dwordx4 v[216:219], v69, s[14:15] offset:1024
	global_load_dwordx4 v[220:223], v69, s[14:15] offset:2048
	global_load_dwordx4 v[224:227], v69, s[14:15] offset:3072
	s_add_u32 s14, s14, 0x1000
	s_addc_u32 s15, s15, 0
	s_waitcnt vmcnt(20)
	v_mfma_f32_16x16x32_bf16 v[0:3], v[76:79], v[108:111], 0
	v_mfma_f32_16x16x32_bf16 v[4:7], v[76:79], v[112:115], 0
	v_mfma_f32_16x16x32_bf16 v[8:11], v[80:83], v[108:111], 0
	v_mfma_f32_16x16x32_bf16 v[12:15], v[80:83], v[112:115], 0
	v_mfma_f32_16x16x32_bf16 v[16:19], v[84:87], v[108:111], 0
	v_mfma_f32_16x16x32_bf16 v[20:23], v[84:87], v[112:115], 0
	v_mfma_f32_16x16x32_bf16 v[24:27], v[88:91], v[108:111], 0
	v_mfma_f32_16x16x32_bf16 v[28:31], v[88:91], v[112:115], 0
	v_mfma_f32_16x16x32_bf16 v[32:35], v[92:95], v[108:111], 0
	v_mfma_f32_16x16x32_bf16 v[36:39], v[92:95], v[112:115], 0
	v_mfma_f32_16x16x32_bf16 v[40:43], v[96:99], v[108:111], 0
	v_mfma_f32_16x16x32_bf16 v[44:47], v[96:99], v[112:115], 0
	v_mfma_f32_16x16x32_bf16 v[48:51], v[100:103], v[108:111], 0
	v_mfma_f32_16x16x32_bf16 v[52:55], v[100:103], v[112:115], 0
	v_mfma_f32_16x16x32_bf16 v[56:59], v[104:107], v[108:111], 0
	v_mfma_f32_16x16x32_bf16 v[60:63], v[104:107], v[112:115], 0
	v_mfma_f32_16x16x32_bf16 v[0:3], v[116:119], v[148:151], v[0:3]
	v_mfma_f32_16x16x32_bf16 v[4:7], v[116:119], v[152:155], v[4:7]
	v_mfma_f32_16x16x32_bf16 v[8:11], v[120:123], v[148:151], v[8:11]
	v_mfma_f32_16x16x32_bf16 v[12:15], v[120:123], v[152:155], v[12:15]
	v_mfma_f32_16x16x32_bf16 v[16:19], v[124:127], v[148:151], v[16:19]
	v_mfma_f32_16x16x32_bf16 v[20:23], v[124:127], v[152:155], v[20:23]
	v_mfma_f32_16x16x32_bf16 v[24:27], v[128:131], v[148:151], v[24:27]
	v_mfma_f32_16x16x32_bf16 v[28:31], v[128:131], v[152:155], v[28:31]
	v_mfma_f32_16x16x32_bf16 v[32:35], v[132:135], v[148:151], v[32:35]
	v_mfma_f32_16x16x32_bf16 v[36:39], v[132:135], v[152:155], v[36:39]
; #define SK_LOAD(buf, c) do { _Pragma("unroll") for (int nt = 0; nt < 2; ++nt) fb[buf][nt] = *(const bf16x8*)(pb + nt * rs + 32 * (c)); \
;         _Pragma("unroll") for (int mt = 0; mt < NMT; ++mt) fa[buf][mt] = *(const bf16x8*)(pa + mt * rs + 32 * (c)); } while (0)
; #define SK_MMA(buf) do { _Pragma("unroll") for (int mt = 0; mt < NMT; ++mt) _Pragma("unroll") for (int nt = 0; nt < 2; ++nt) \
;         acc[mt][nt] = __builtin_amdgcn_mfma_f32_16x16x32_bf16(fa[buf][mt], fb[buf][nt], acc[mt][nt], 0, 0, 0); } while (0)
; template <int MT, class Epi>
; DI void skinny_unit(LAS unsigned char* lds, const bf16_t* A, const bf16_t* Wt, int K, int cgi, int k0, int row0, const Epi& E, int tid) {
;     ...
;     SK_LOAD(0, 0); SK_LOAD(1, 1);
;     SK_LOAD(2, 2); SK_MMA(0);
;     SK_LOAD(0, 3); SK_MMA(1);
;     SK_LOAD(1, 4); SK_MMA(2);
;     SK_LOAD(2, 5); SK_MMA(0);
;     SK_LOAD(0, 6); SK_MMA(1);
;     SK_LOAD(1, 7); SK_MMA(2);
;     SK_MMA(0); SK_MMA(1);
	v_mfma_f32_16x16x32_bf16 v[40:43], v[136:139], v[148:151], v[40:43]
	v_mfma_f32_16x16x32_bf16 v[44:47], v[136:139], v[152:155], v[44:47]
	v_mfma_f32_16x16x32_bf16 v[48:51], v[140:143], v[148:151], v[48:51]
	v_mfma_f32_16x16x32_bf16 v[52:55], v[140:143], v[152:155], v[52:55]
	v_mfma_f32_16x16x32_bf16 v[56:59], v[144:147], v[148:151], v[56:59]
	v_mfma_f32_16x16x32_bf16 v[60:63], v[144:147], v[152:155], v[60:63]
	global_load_dwordx4 v[108:111], v64, s[8:9] offset:256 nt
	global_load_dwordx4 v[148:151], v64, s[8:9] offset:320 nt
	global_load_dwordx4 v[112:115], v64, s[10:11] offset:256 nt
	global_load_dwordx4 v[152:155], v64, s[10:11] offset:320 nt
	global_load_dwordx4 v[76:79], v69, s[14:15] offset:0
	global_load_dwordx4 v[80:83], v69, s[14:15] offset:1024
	global_load_dwordx4 v[84:87], v69, s[14:15] offset:2048
	global_load_dwordx4 v[88:91], v69, s[14:15] offset:3072
	s_add_u32 s14, s14, 0x1000
	s_addc_u32 s15, s15, 0
	global_load_dwordx4 v[92:95], v69, s[14:15] offset:0
	global_load_dwordx4 v[96:99], v69, s[14:15] offset:1024
	global_load_dwordx4 v[100:103], v69, s[14:15] offset:2048
	global_load_dwordx4 v[104:107], v69, s[14:15] offset:3072
	s_add_u32 s14, s14, 0x1000
	s_addc_u32 s15, s15, 0
	global_load_dwordx4 v[116:119], v69, s[14:15] offset:0
	global_load_dwordx4 v[120:123], v69, s[14:15] offset:1024
	global_load_dwordx4 v[124:127], v69, s[14:15] offset:2048
	global_load_dwordx4 v[128:131], v69, s[14:15] offset:3072
	s_add_u32 s14, s14, 0x1000
	s_addc_u32 s15, s15, 0
	global_load_dwordx4 v[132:135], v69, s[14:15] offset:0
	global_load_dwordx4 v[136:139], v69, s[14:15] offset:1024
	global_load_dwordx4 v[140:143], v69, s[14:15] offset:2048
	global_load_dwordx4 v[144:147], v69, s[14:15] offset:3072
	s_add_u32 s14, s14, 0x1000
	s_addc_u32 s15, s15, 0
	s_waitcnt vmcnt(20)
	v_mfma_f32_16x16x32_bf16 v[0:3], v[156:159], v[188:191], v[0:3]
	v_mfma_f32_16x16x32_bf16 v[4:7], v[156:159], v[192:195], v[4:7]
	v_mfma_f32_16x16x32_bf16 v[8:11], v[160:163], v[188:191], v[8:11]
	v_mfma_f32_16x16x32_bf16 v[12:15], v[160:163], v[192:195], v[12:15]
	v_mfma_f32_16x16x32_bf16 v[16:19], v[164:167], v[188:191], v[16:19]
	v_mfma_f32_16x16x32_bf16 v[20:23], v[164:167], v[192:195], v[20:23]
	v_mfma_f32_16x16x32_bf16 v[24:27], v[168:171], v[188:191], v[24:27]
	v_mfma_f32_16x16x32_bf16 v[28:31], v[168:171], v[192:195], v[28:31]
	v_mfma_f32_16x16x32_bf16 v[32:35], v[172:175], v[188:191], v[32:35]
	v_mfma_f32_16x16x32_bf16 v[36:39], v[172:175], v[192:195], v[36:39]
	v_mfma_f32_16x16x32_bf16 v[40:43], v[176:179], v[188:191], v[40:43]
	v_mfma_f32_16x16x32_bf16 v[44:47], v[176:179], v[192:195], v[44:47]
	v_mfma_f32_16x16x32_bf16 v[48:51], v[180:183], v[188:191], v[48:51]
	v_mfma_f32_16x16x32_bf16 v[52:55], v[180:183], v[192:195], v[52:55]
	v_mfma_f32_16x16x32_bf16 v[56:59], v[184:187], v[188:191], v[56:59]
	v_mfma_f32_16x16x32_bf16 v[60:63], v[184:187], v[192:195], v[60:63]
	v_mfma_f32_16x16x32_bf16 v[0:3], v[196:199], v[228:231], v[0:3]
	v_mfma_f32_16x16x32_bf16 v[4:7], v[196:199], v[232:235], v[4:7]
	v_mfma_f32_16x16x32_bf16 v[8:11], v[200:203], v[228:231], v[8:11]
	v_mfma_f32_16x16x32_bf16 v[12:15], v[200:203], v[232:235], v[12:15]
	v_mfma_f32_16x16x32_bf16 v[16:19], v[204:207], v[228:231], v[16:19]
	v_mfma_f32_16x16x32_bf16 v[20:23], v[204:207], v[232:235], v[20:23]
	v_mfma_f32_16x16x32_bf16 v[24:27], v[208:211], v[228:231], v[24:27]
	v_mfma_f32_16x16x32_bf16 v[28:31], v[208:211], v[232:235], v[28:31]
	v_mfma_f32_16x16x32_bf16 v[32:35], v[212:215], v[228:231], v[32:35]
	v_mfma_f32_16x16x32_bf16 v[36:39], v[212:215], v[232:235], v[36:39]
	v_mfma_f32_16x16x32_bf16 v[40:43], v[216:219], v[228:231], v[40:43]
	v_mfma_f32_16x16x32_bf16 v[44:47], v[216:219], v[232:235], v[44:47]
	v_mfma_f32_16x16x32_bf16 v[48:51], v[220:223], v[228:231], v[48:51]
	v_mfma_f32_16x16x32_bf16 v[52:55], v[220:223], v[232:235], v[52:55]
	v_mfma_f32_16x16x32_bf16 v[56:59], v[224:227], v[228:231], v[56:59]
	v_mfma_f32_16x16x32_bf16 v[60:63], v[224:227], v[232:235], v[60:63]
	global_load_dwordx4 v[188:191], v64, s[8:9] offset:384 nt
	global_load_dwordx4 v[228:231], v64, s[8:9] offset:448 nt
	global_load_dwordx4 v[192:195], v64, s[10:11] offset:384 nt
	global_load_dwordx4 v[232:235], v64, s[10:11] offset:448 nt
	global_load_dwordx4 v[156:159], v69, s[14:15] offset:0
	global_load_dwordx4 v[160:163], v69, s[14:15] offset:1024
	global_load_dwordx4 v[164:167], v69, s[14:15] offset:2048
	global_load_dwordx4 v[168:171], v69, s[14:15] offset:3072
	s_add_u32 s14, s14, 0x1000
	s_addc_u32 s15, s15, 0
	global_load_dwordx4 v[172:175], v69, s[14:15] offset:0
	global_load_dwordx4 v[176:179], v69, s[14:15] offset:1024
	global_load_dwordx4 v[180:183], v69, s[14:15] offset:2048
	global_load_dwordx4 v[184:187], v69, s[14:15] offset:3072
	s_add_u32 s14, s14, 0x1000
	s_addc_u32 s15, s15, 0
	global_load_dwordx4 v[196:199], v69, s[14:15] offset:0
	global_load_dwordx4 v[200:203], v69, s[14:15] offset:1024
	global_load_dwordx4 v[204:207], v69, s[14:15] offset:2048
	global_load_dwordx4 v[208:211], v69, s[14:15] offset:3072
	s_add_u32 s14, s14, 0x1000
	s_addc_u32 s15, s15, 0
	global_load_dwordx4 v[212:215], v69, s[14:15] offset:0
	global_load_dwordx4 v[216:219], v69, s[14:15] offset:1024
	global_load_dwordx4 v[220:223], v69, s[14:15] offset:2048
	global_load_dwordx4 v[224:227], v69, s[14:15] offset:3072
	s_waitcnt vmcnt(20)
; #define LAS __attribute__((address_space(3)))
; #define SK_LOAD(buf, c) do { _Pragma("unroll") for (int nt = 0; nt < 2; ++nt) fb[buf][nt] = *(const bf16x8*)(pb + nt * rs + 32 * (c)); \
;         _Pragma("unroll") for (int mt = 0; mt < NMT; ++mt) fa[buf][mt] = *(const bf16x8*)(pa + mt * rs + 32 * (c)); } while (0)
; #define SK_MMA(buf) do { _Pragma("unroll") for (int mt = 0; mt < NMT; ++mt) _Pragma("unroll") for (int nt = 0; nt < 2; ++nt) \
;         acc[mt][nt] = __builtin_amdgcn_mfma_f32_16x16x32_bf16(fa[buf][mt], fb[buf][nt], acc[mt][nt], 0, 0, 0); } while (0)
; template <int MT, class Epi>
; DI void skinny_unit(LAS unsigned char* lds, const bf16_t* A, const bf16_t* Wt, int K, int cgi, int k0, int row0, const Epi& E, int tid) {
;     ...
;     SK_LOAD(0, 0); SK_LOAD(1, 1);
;     SK_LOAD(2, 2); SK_MMA(0);
;     SK_LOAD(0, 3); SK_MMA(1);
;     SK_LOAD(1, 4); SK_MMA(2);
;     SK_LOAD(2, 5); SK_MMA(0);
;     SK_LOAD(0, 6); SK_MMA(1);
;     SK_LOAD(1, 7); SK_MMA(2);
;     SK_MMA(0); SK_MMA(1);
;     ...
;     constexpr int NR = 32 * MT;
;     LAS float* red = (LAS float*)lds;
; #pragma unroll
;     for (int mt = 0; mt < NMT; ++mt)
; #pragma unroll
;         for (int nt = 0; nt < 2; ++nt)
; #pragma unroll
;             for (int j = 0; j < 4; ++j) red[(wid * NR + mt * 16 + 4 * fq + j) * 32 + nt * 16 + fr] = acc[mt][nt][j];
	v_mfma_f32_16x16x32_bf16 v[0:3], v[76:79], v[108:111], v[0:3]
	v_mfma_f32_16x16x32_bf16 v[4:7], v[76:79], v[112:115], v[4:7]
	v_mfma_f32_16x16x32_bf16 v[8:11], v[80:83], v[108:111], v[8:11]
	v_mfma_f32_16x16x32_bf16 v[12:15], v[80:83], v[112:115], v[12:15]
	v_mfma_f32_16x16x32_bf16 v[16:19], v[84:87], v[108:111], v[16:19]
	v_mfma_f32_16x16x32_bf16 v[20:23], v[84:87], v[112:115], v[20:23]
	v_mfma_f32_16x16x32_bf16 v[24:27], v[88:91], v[108:111], v[24:27]
	v_mfma_f32_16x16x32_bf16 v[28:31], v[88:91], v[112:115], v[28:31]
	v_mfma_f32_16x16x32_bf16 v[32:35], v[92:95], v[108:111], v[32:35]
	v_mfma_f32_16x16x32_bf16 v[36:39], v[92:95], v[112:115], v[36:39]
	v_mfma_f32_16x16x32_bf16 v[40:43], v[96:99], v[108:111], v[40:43]
	v_mfma_f32_16x16x32_bf16 v[44:47], v[96:99], v[112:115], v[44:47]
	v_mfma_f32_16x16x32_bf16 v[48:51], v[100:103], v[108:111], v[48:51]
	v_mfma_f32_16x16x32_bf16 v[52:55], v[100:103], v[112:115], v[52:55]
	v_mfma_f32_16x16x32_bf16 v[56:59], v[104:107], v[108:111], v[56:59]
	v_mfma_f32_16x16x32_bf16 v[60:63], v[104:107], v[112:115], v[60:63]
	v_mfma_f32_16x16x32_bf16 v[0:3], v[116:119], v[148:151], v[0:3]
	v_mfma_f32_16x16x32_bf16 v[4:7], v[116:119], v[152:155], v[4:7]
	v_mfma_f32_16x16x32_bf16 v[8:11], v[120:123], v[148:151], v[8:11]
	v_mfma_f32_16x16x32_bf16 v[12:15], v[120:123], v[152:155], v[12:15]
	v_mfma_f32_16x16x32_bf16 v[16:19], v[124:127], v[148:151], v[16:19]
	v_mfma_f32_16x16x32_bf16 v[20:23], v[124:127], v[152:155], v[20:23]
	v_mfma_f32_16x16x32_bf16 v[24:27], v[128:131], v[148:151], v[24:27]
	v_mfma_f32_16x16x32_bf16 v[28:31], v[128:131], v[152:155], v[28:31]
	v_mfma_f32_16x16x32_bf16 v[32:35], v[132:135], v[148:151], v[32:35]
	v_mfma_f32_16x16x32_bf16 v[36:39], v[132:135], v[152:155], v[36:39]
	v_mfma_f32_16x16x32_bf16 v[40:43], v[136:139], v[148:151], v[40:43]
	v_mfma_f32_16x16x32_bf16 v[44:47], v[136:139], v[152:155], v[44:47]
	v_mfma_f32_16x16x32_bf16 v[48:51], v[140:143], v[148:151], v[48:51]
	v_mfma_f32_16x16x32_bf16 v[52:55], v[140:143], v[152:155], v[52:55]
	v_mfma_f32_16x16x32_bf16 v[56:59], v[144:147], v[148:151], v[56:59]
	v_mfma_f32_16x16x32_bf16 v[60:63], v[144:147], v[152:155], v[60:63]
	s_waitcnt vmcnt(0)
	v_mfma_f32_16x16x32_bf16 v[0:3], v[156:159], v[188:191], v[0:3]
	v_mfma_f32_16x16x32_bf16 v[4:7], v[156:159], v[192:195], v[4:7]
	v_mfma_f32_16x16x32_bf16 v[8:11], v[160:163], v[188:191], v[8:11]
	v_mfma_f32_16x16x32_bf16 v[12:15], v[160:163], v[192:195], v[12:15]
	v_mfma_f32_16x16x32_bf16 v[16:19], v[164:167], v[188:191], v[16:19]
	v_mfma_f32_16x16x32_bf16 v[20:23], v[164:167], v[192:195], v[20:23]
	v_mfma_f32_16x16x32_bf16 v[24:27], v[168:171], v[188:191], v[24:27]
	v_mfma_f32_16x16x32_bf16 v[28:31], v[168:171], v[192:195], v[28:31]
	v_mfma_f32_16x16x32_bf16 v[32:35], v[172:175], v[188:191], v[32:35]
	v_mfma_f32_16x16x32_bf16 v[36:39], v[172:175], v[192:195], v[36:39]
	v_mfma_f32_16x16x32_bf16 v[40:43], v[176:179], v[188:191], v[40:43]
	v_mfma_f32_16x16x32_bf16 v[44:47], v[176:179], v[192:195], v[44:47]
	v_mfma_f32_16x16x32_bf16 v[48:51], v[180:183], v[188:191], v[48:51]
	v_mfma_f32_16x16x32_bf16 v[52:55], v[180:183], v[192:195], v[52:55]
	v_mfma_f32_16x16x32_bf16 v[56:59], v[184:187], v[188:191], v[56:59]
	v_mfma_f32_16x16x32_bf16 v[60:63], v[184:187], v[192:195], v[60:63]
	v_mfma_f32_16x16x32_bf16 v[0:3], v[196:199], v[228:231], v[0:3]
	v_mfma_f32_16x16x32_bf16 v[4:7], v[196:199], v[232:235], v[4:7]
	v_mfma_f32_16x16x32_bf16 v[8:11], v[200:203], v[228:231], v[8:11]
	v_mfma_f32_16x16x32_bf16 v[12:15], v[200:203], v[232:235], v[12:15]
	v_mfma_f32_16x16x32_bf16 v[16:19], v[204:207], v[228:231], v[16:19]
	v_mfma_f32_16x16x32_bf16 v[20:23], v[204:207], v[232:235], v[20:23]
	v_mfma_f32_16x16x32_bf16 v[24:27], v[208:211], v[228:231], v[24:27]
	v_mfma_f32_16x16x32_bf16 v[28:31], v[208:211], v[232:235], v[28:31]
	v_mfma_f32_16x16x32_bf16 v[32:35], v[212:215], v[228:231], v[32:35]
	v_mfma_f32_16x16x32_bf16 v[36:39], v[212:215], v[232:235], v[36:39]
	v_mfma_f32_16x16x32_bf16 v[40:43], v[216:219], v[228:231], v[40:43]
	v_mfma_f32_16x16x32_bf16 v[44:47], v[216:219], v[232:235], v[44:47]
	v_mfma_f32_16x16x32_bf16 v[48:51], v[220:223], v[228:231], v[48:51]
	v_mfma_f32_16x16x32_bf16 v[52:55], v[220:223], v[232:235], v[52:55]
	v_mfma_f32_16x16x32_bf16 v[56:59], v[224:227], v[228:231], v[56:59]
	v_mfma_f32_16x16x32_bf16 v[60:63], v[224:227], v[232:235], v[60:63]
	v_add_u32_e32 v77, 0x800, v65
	v_add_u32_e32 v78, 0x1000, v65
	v_add_u32_e32 v79, 0x1800, v65
	v_add_u32_e32 v80, 0x2000, v65
	v_add_u32_e32 v81, 0x2800, v65
	v_add_u32_e32 v82, 0x3000, v65
	v_add_u32_e32 v83, 0x3800, v65
	s_nop 7
	s_nop 3
	ds_write2_b32 v65, v0, v4 offset1:16
	ds_write2_b32 v65, v1, v5 offset0:32 offset1:48
	ds_write2_b32 v65, v2, v6 offset0:64 offset1:80
	ds_write2_b32 v65, v3, v7 offset0:96 offset1:112
	ds_write2_b32 v77, v8, v12 offset1:16
	ds_write2_b32 v77, v9, v13 offset0:32 offset1:48
	ds_write2_b32 v77, v10, v14 offset0:64 offset1:80
	ds_write2_b32 v77, v11, v15 offset0:96 offset1:112
	ds_write2_b32 v78, v16, v20 offset1:16
	ds_write2_b32 v78, v17, v21 offset0:32 offset1:48
	ds_write2_b32 v78, v18, v22 offset0:64 offset1:80
	ds_write2_b32 v78, v19, v23 offset0:96 offset1:112
	ds_write2_b32 v79, v24, v28 offset1:16
	ds_write2_b32 v79, v25, v29 offset0:32 offset1:48
	ds_write2_b32 v79, v26, v30 offset0:64 offset1:80
	ds_write2_b32 v79, v27, v31 offset0:96 offset1:112
	ds_write2_b32 v80, v32, v36 offset1:16
	ds_write2_b32 v80, v33, v37 offset0:32 offset1:48
	ds_write2_b32 v80, v34, v38 offset0:64 offset1:80
	ds_write2_b32 v80, v35, v39 offset0:96 offset1:112
	ds_write2_b32 v81, v40, v44 offset1:16
	ds_write2_b32 v81, v41, v45 offset0:32 offset1:48
	ds_write2_b32 v81, v42, v46 offset0:64 offset1:80
	ds_write2_b32 v81, v43, v47 offset0:96 offset1:112
	ds_write2_b32 v82, v48, v52 offset1:16
	ds_write2_b32 v82, v49, v53 offset0:32 offset1:48
	ds_write2_b32 v82, v50, v54 offset0:64 offset1:80
	ds_write2_b32 v82, v51, v55 offset0:96 offset1:112
	ds_write2_b32 v83, v56, v60 offset1:16
	ds_write2_b32 v83, v57, v61 offset0:32 offset1:48
	ds_write2_b32 v83, v58, v62 offset0:64 offset1:80
	ds_write2_b32 v83, v59, v63 offset0:96 offset1:112
	s_waitcnt lgkmcnt(0)
	s_barrier
; #define LAS __attribute__((address_space(3)))
; template <int MT, class Epi>
; DI void skinny_unit(LAS unsigned char* lds, const bf16_t* A, const bf16_t* Wt, int K, int cgi, int k0, int row0, const Epi& E, int tid) {
;     ...
;     if (MT == 4) {
;         const int row = tid >> 2, c8 = (tid & 3) * 8;
;         f32x4 sa = {0.f, 0.f, 0.f, 0.f}, sb = {0.f, 0.f, 0.f, 0.f};
; #pragma unroll
;         for (int w = 0; w < 8; ++w) { sa += *(const LAS f32x4*)(red + (w * NR + row) * 32 + c8); sb += *(const LAS f32x4*)(red + (w * NR + row) * 32 + c8 + 4); }
;         E(row0 + row, c0 + c8, sa); E(row0 + row, c0 + c8 + 4, sb);
	ds_read_b128 v[76:79], v66 offset:0
	ds_read_b128 v[80:83], v66 offset:16
	ds_read_b128 v[84:87], v66 offset:16384
	ds_read_b128 v[88:91], v66 offset:16400
	ds_read_b128 v[92:95], v66 offset:32768
	ds_read_b128 v[96:99], v66 offset:32784
	ds_read_b128 v[100:103], v66 offset:49152
	ds_read_b128 v[104:107], v66 offset:49168
	ds_read_b128 v[108:111], v67 offset:0
	ds_read_b128 v[112:115], v67 offset:16
	ds_read_b128 v[116:119], v67 offset:16384
	ds_read_b128 v[120:123], v67 offset:16400
	ds_read_b128 v[124:127], v67 offset:32768
	ds_read_b128 v[128:131], v67 offset:32784
	ds_read_b128 v[132:135], v67 offset:49152
	ds_read_b128 v[136:139], v67 offset:49168
	s_waitcnt lgkmcnt(12)
	v_pk_add_f32 v[76:77], v[76:77], v[84:85]
	v_pk_add_f32 v[78:79], v[78:79], v[86:87]
	v_pk_add_f32 v[80:81], v[80:81], v[88:89]
	v_pk_add_f32 v[82:83], v[82:83], v[90:91]
	s_waitcnt lgkmcnt(10)
	v_pk_add_f32 v[76:77], v[76:77], v[92:93]
	v_pk_add_f32 v[78:79], v[78:79], v[94:95]
	v_pk_add_f32 v[80:81], v[80:81], v[96:97]
	v_pk_add_f32 v[82:83], v[82:83], v[98:99]
	s_waitcnt lgkmcnt(8)
	v_pk_add_f32 v[76:77], v[76:77], v[100:101]
	v_pk_add_f32 v[78:79], v[78:79], v[102:103]
	v_pk_add_f32 v[80:81], v[80:81], v[104:105]
	v_pk_add_f32 v[82:83], v[82:83], v[106:107]
	s_waitcnt lgkmcnt(6)
	v_pk_add_f32 v[76:77], v[76:77], v[108:109]
	v_pk_add_f32 v[78:79], v[78:79], v[110:111]
	v_pk_add_f32 v[80:81], v[80:81], v[112:113]
	v_pk_add_f32 v[82:83], v[82:83], v[114:115]
	s_waitcnt lgkmcnt(4)
	v_pk_add_f32 v[76:77], v[76:77], v[116:117]
	v_pk_add_f32 v[78:79], v[78:79], v[118:119]
	v_pk_add_f32 v[80:81], v[80:81], v[120:121]
	v_pk_add_f32 v[82:83], v[82:83], v[122:123]
	s_waitcnt lgkmcnt(2)
	v_pk_add_f32 v[76:77], v[76:77], v[124:125]
	v_pk_add_f32 v[78:79], v[78:79], v[126:127]
	v_pk_add_f32 v[80:81], v[80:81], v[128:129]
	v_pk_add_f32 v[82:83], v[82:83], v[130:131]
	s_waitcnt lgkmcnt(0)
	v_pk_add_f32 v[76:77], v[76:77], v[132:133]
	v_pk_add_f32 v[78:79], v[78:79], v[134:135]
	v_pk_add_f32 v[80:81], v[80:81], v[136:137]
	v_pk_add_f32 v[82:83], v[82:83], v[138:139]
	v_max_f32_e32 v76, 0, v76
	v_max_f32_e32 v77, 0, v77
	v_max_f32_e32 v78, 0, v78
	v_max_f32_e32 v79, 0, v79
	v_max_f32_e32 v80, 0, v80
	v_max_f32_e32 v81, 0, v81
	v_max_f32_e32 v82, 0, v82
	v_max_f32_e32 v83, 0, v83
	v_pk_mul_f32 v[76:77], v[76:77], v[76:77]
	v_pk_mul_f32 v[78:79], v[78:79], v[78:79]
	v_pk_mul_f32 v[80:81], v[80:81], v[80:81]
	v_pk_mul_f32 v[82:83], v[82:83], v[82:83]
	v_cvt_pk_bf16_f32 v84, v76, v77
	v_cvt_pk_bf16_f32 v85, v78, v79
	v_cvt_pk_bf16_f32 v86, v80, v81
	v_cvt_pk_bf16_f32 v87, v82, v83
	global_store_dwordx4 v68, v[84:87], s[12:13]
	s_add_i32 s0, s0, s64
	s_cmpk_lt_i32 s0, 0x100
	s_barrier
	s_cbranch_scc1 .Lsk6_loop
